# attention DMA loop: 64-bit address advances (6 instead of 18 instructions per iteration)
# speedup vs baseline: 1.0003x; 1.0003x over previous
; __device__ __forceinline__ void attn_unit(LAS char* lds, const bf16_t* Qp, const bf16_t* KVp, const bf16_t* KRp, int ntiles, bf16_t* Yp, bool dry) {
;     ...
;     const bf16_t* gk = KVp + (size_t)krow * 1024 + kc * 8;
;     const bf16_t* gv = gk + 512;
;     const bf16_t* gr = KRp + (size_t)rrow * 32 + rc * 8;
;     const int lk = krow * AK_PITCH + kc * 16, lr = rrow * AK_PITCH + 128 + rc * 16, lv = (kc >> 2) * 4096 + krow * 64 + (kc & 3) * 16;
;     const bool rth = tid < 256;
;     u32x4 skA, svA, srA = {0u, 0u, 0u, 0u}, skB, svB, srB = {0u, 0u, 0u, 0u};
.Latt_iter:
	s_waitcnt vmcnt(0)
	v_xor_b32_e32 v82, 0x80000000, v189
	v_mov_b32_e32 v83, v82
	v_mov_b32_e32 v84, v82
	v_mov_b32_e32 v85, v82
	v_mov_b32_e32 v86, v82
	v_mov_b32_e32 v87, v82
	v_mov_b32_e32 v88, v82
	v_mov_b32_e32 v89, v82
	v_mov_b32_e32 v90, v82
	v_mov_b32_e32 v91, v82
	v_mov_b32_e32 v92, v82
	v_mov_b32_e32 v93, v82
	v_mov_b32_e32 v94, v82
	v_mov_b32_e32 v95, v82
	v_mov_b32_e32 v96, v82
	v_mov_b32_e32 v97, v82
	s_ashr_i32 s14, s8, 6
	s_mul_i32 s2, s14, 0x480000
	s_bfe_u32 s15, s8, 0x30003
	s_lshl_b32 s15, s15, 7
	s_add_i32 s2, s2, s15
	s_add_u32 s2, s2, 0x2f440000
	s_add_u32 s2, s88, s2
	s_addc_u32 s3, s89, 0
	s_mul_i32 s16, s14, 0x24000
	s_add_u32 s16, s16, 0x3cc02000
	s_add_u32 s16, s88, s16
	s_addc_u32 s17, s89, 0
	v_mov_b32_e32 v180, 0x40000
	v_mov_b32_e32 v181, 0x2000
	v_mov_b32_e32 v212, v182
	v_cmp_lt_u32_e32 vcc, 831, v212
	v_cndmask_b32_e64 v213, 0, 1, vcc
	v_mul_u32_u24_e32 v214, 832, v213
	v_sub_u32_e32 v212, v212, v214
	v_mul_u32_u24_e32 v214, 5042, v212
	v_lshrrev_b32_e32 v214, 16, v214
	v_mul_u32_u24_e32 v215, 13, v214
	v_sub_u32_e32 v215, v212, v215
	v_cmp_eq_u32_e32 vcc, 12, v215
	v_cndmask_b32_e64 v215, v215, 0, vcc
	v_lshlrev_b32_e32 v150, 17, v213
	v_lshl_add_u32 v150, v214, 11, v150
	v_lshl_add_u32 v150, v215, 4, v150
	v_lshlrev_b32_e32 v151, 12, v213
	v_lshl_add_u32 v151, v214, 6, v151
	v_lshl_add_u32 v151, v215, 4, v151
	v_add_u32_e32 v151, 0xffffff80, v151
	v_cmp_lt_u32_e64 s[14:15], 7, v215
	v_cndmask_b32_e64 v150, v150, v151, s[14:15]
	v_mov_b32_e32 v152, s2
	v_mov_b32_e32 v153, s3
	v_mov_b32_e32 v178, s16
	v_mov_b32_e32 v179, s17
	v_cndmask_b32_e64 v152, v152, v178, s[14:15]
	v_cndmask_b32_e64 v153, v153, v179, s[14:15]
	v_cndmask_b32_e64 v142, v180, v181, s[14:15]
	v_mov_b32_e32 v143, 0
	v_add_co_u32_e32 v130, vcc, v150, v152
	s_nop 1
	v_addc_co_u32_e32 v131, vcc, 0, v153, vcc
	v_add_u32_e32 v212, 512, v182
	v_cmp_lt_u32_e32 vcc, 831, v212
	v_cndmask_b32_e64 v213, 0, 1, vcc
	v_mul_u32_u24_e32 v214, 832, v213
	v_sub_u32_e32 v212, v212, v214
	v_mul_u32_u24_e32 v214, 5042, v212
	v_lshrrev_b32_e32 v214, 16, v214
	v_mul_u32_u24_e32 v215, 13, v214
	v_sub_u32_e32 v215, v212, v215
	v_cmp_eq_u32_e32 vcc, 12, v215
	v_cndmask_b32_e64 v215, v215, 0, vcc
	v_lshlrev_b32_e32 v150, 17, v213
	v_lshl_add_u32 v150, v214, 11, v150
	v_lshl_add_u32 v150, v215, 4, v150
	v_lshlrev_b32_e32 v151, 12, v213
	v_lshl_add_u32 v151, v214, 6, v151
	v_lshl_add_u32 v151, v215, 4, v151
	v_add_u32_e32 v151, 0xffffff80, v151
	v_cmp_lt_u32_e64 s[14:15], 7, v215
	v_cndmask_b32_e64 v150, v150, v151, s[14:15]
	v_mov_b32_e32 v152, s2
	v_mov_b32_e32 v153, s3
	v_mov_b32_e32 v178, s16
	v_mov_b32_e32 v179, s17
	v_cndmask_b32_e64 v152, v152, v178, s[14:15]
	v_cndmask_b32_e64 v153, v153, v179, s[14:15]
	v_cndmask_b32_e64 v144, v180, v181, s[14:15]
	v_mov_b32_e32 v145, 0
	v_add_co_u32_e32 v132, vcc, v150, v152
	s_nop 1
	v_addc_co_u32_e32 v133, vcc, 0, v153, vcc
	v_add_u32_e32 v212, 1024, v182
	v_cmp_lt_u32_e32 vcc, 831, v212
	v_cndmask_b32_e64 v213, 0, 1, vcc
	v_mul_u32_u24_e32 v214, 832, v213
	v_sub_u32_e32 v212, v212, v214
	v_mul_u32_u24_e32 v214, 5042, v212
	v_lshrrev_b32_e32 v214, 16, v214
	v_mul_u32_u24_e32 v215, 13, v214
	v_sub_u32_e32 v215, v212, v215
	v_cmp_eq_u32_e32 vcc, 12, v215
	v_cndmask_b32_e64 v215, v215, 0, vcc
	v_lshlrev_b32_e32 v150, 17, v213
	v_lshl_add_u32 v150, v214, 11, v150
	v_lshl_add_u32 v150, v215, 4, v150
	v_lshlrev_b32_e32 v151, 12, v213
	v_lshl_add_u32 v151, v214, 6, v151
	v_lshl_add_u32 v151, v215, 4, v151
	v_add_u32_e32 v151, 0xffffff80, v151
	v_cmp_lt_u32_e64 s[14:15], 7, v215
	v_cndmask_b32_e64 v150, v150, v151, s[14:15]
	v_mov_b32_e32 v152, s2
	v_mov_b32_e32 v153, s3
	v_mov_b32_e32 v178, s16
	v_mov_b32_e32 v179, s17
	v_cndmask_b32_e64 v152, v152, v178, s[14:15]
	v_cndmask_b32_e64 v153, v153, v179, s[14:15]
	v_cndmask_b32_e64 v146, v180, v181, s[14:15]
	v_mov_b32_e32 v147, 0
	v_add_co_u32_e32 v134, vcc, v150, v152
	s_nop 1
	v_addc_co_u32_e32 v135, vcc, 0, v153, vcc
	v_add_u32_e32 v212, 1536, v182
	v_cmp_lt_u32_e32 vcc, 831, v212
	v_cndmask_b32_e64 v213, 0, 1, vcc
	v_mul_u32_u24_e32 v214, 832, v213
	v_sub_u32_e32 v212, v212, v214
	v_mul_u32_u24_e32 v214, 5042, v212
	v_lshrrev_b32_e32 v214, 16, v214
	v_mul_u32_u24_e32 v215, 13, v214
	v_sub_u32_e32 v215, v212, v215
	v_cmp_eq_u32_e32 vcc, 12, v215
	v_cndmask_b32_e64 v215, v215, 0, vcc
	v_lshlrev_b32_e32 v150, 17, v213
	v_lshl_add_u32 v150, v214, 11, v150
	v_lshl_add_u32 v150, v215, 4, v150
	v_lshlrev_b32_e32 v151, 12, v213
	v_lshl_add_u32 v151, v214, 6, v151
	v_lshl_add_u32 v151, v215, 4, v151
	v_add_u32_e32 v151, 0xffffff80, v151
	v_cmp_lt_u32_e64 s[14:15], 7, v215
	v_cndmask_b32_e64 v150, v150, v151, s[14:15]
	v_mov_b32_e32 v152, s2
	v_mov_b32_e32 v153, s3
	v_mov_b32_e32 v178, s16
	v_mov_b32_e32 v179, s17
	v_cndmask_b32_e64 v152, v152, v178, s[14:15]
	v_cndmask_b32_e64 v153, v153, v179, s[14:15]
	v_cndmask_b32_e64 v148, v180, v181, s[14:15]
	v_mov_b32_e32 v149, 0
	v_add_co_u32_e32 v136, vcc, v150, v152
	s_nop 1
	v_addc_co_u32_e32 v137, vcc, 0, v153, vcc
	v_bfe_u32 v212, v182, 6, 2
	v_bfe_u32 v213, v182, 2, 4
	v_lshl_add_u32 v212, v212, 4, v213
	v_bfe_u32 v213, v182, 8, 1
	v_and_b32_e32 v214, 3, v182
	v_lshl_add_u32 v213, v213, 2, v214
	v_lshlrev_b32_e32 v212, 11, v212
	v_lshl_add_u32 v212, v213, 4, v212
	v_add_u32_e32 v212, 0x400, v212
	v_mov_b32_e32 v213, s3
	v_add_co_u32_e32 v138, vcc, s2, v212
	s_nop 1
	v_addc_co_u32_e32 v139, vcc, 0, v213, vcc
	v_add_co_u32_e32 v140, vcc, 0x20000, v138
	s_nop 1
	v_addc_co_u32_e32 v141, vcc, 0, v139, vcc

; #define AT_LOAD(X, t) do { const size_t adv_ = (size_t)(t) * 64; sk##X = *(const u32x4*)(gk + adv_ * 1024); sv##X = *(const u32x4*)(gv + adv_ * 1024); if (rth) sr##X = *(const u32x4*)(gr + adv_ * 32); } while (0)
; __device__ __forceinline__ void attn_unit(LAS char* lds, const bf16_t* Qp, const bf16_t* KVp, const bf16_t* KRp, int ntiles, bf16_t* Yp, bool dry) {
;     ...
;         if (more) { AT_LOAD(A, t + 2); AT_LOAD(B, t + 3); }
.Latt_dk3:
	s_lshl_b32 s15, s14, 13
	s_add_i32 s15, s15, s16
	s_add_i32 s15, s15, 0xd000
	s_mov_b32 m0, s15
	s_add_i32 s15, s15, 0x2000
	global_load_lds_dwordx4 v[138:139], off
	s_mov_b32 m0, s15
	s_nop 0
	global_load_lds_dwordx4 v[140:141], off
	v_lshl_add_u64 v[130:131], v[130:131], 0, v[142:143]
	v_lshl_add_u64 v[132:133], v[132:133], 0, v[144:145]
	v_lshl_add_u64 v[134:135], v[134:135], 0, v[146:147]
	v_lshl_add_u64 v[136:137], v[136:137], 0, v[148:149]
	v_lshl_add_u64 v[138:139], v[138:139], 0, s[26:27]
	v_lshl_add_u64 v[140:141], v[140:141], 0, s[26:27]
